# v025 + w_in L0 epilogues un-aligned (wave groups stay staggered through the epilogue)
# baseline (speedup 1.0000x reference)
.LBB0_258:
	s_and_b64 vcc, exec, s[14:15]
	s_cbranch_vccz .LBB0_260
	s_nop 0

.LBB0_265:
	s_andn2_b64 vcc, exec, s[10:11]
	s_cbranch_vccnz .LBB0_239
	s_nop 0
	s_branch .LBB0_239
.LBB0_267:
	s_and_b64 vcc, exec, s[14:15]
	s_cbranch_vccz .Lae_skip0
	s_barrier
.Lae_skip0:
	s_waitcnt vmcnt(0)
	s_barrier
